# v21 plus align barrier sunk below first epilogue loads in P1/P4/P6 and spin loops without s_sleep
# speedup vs baseline: 1.0002x; 1.0002x over previous
; __device__ __forceinline__ unsigned xb_ld(unsigned* p)              { return __hip_atomic_load(p, __ATOMIC_RELAXED, __HIP_MEMORY_SCOPE_AGENT); }
; __device__ __forceinline__ void xcd_barrier_complete(unsigned* bar, unsigned x, unsigned& nloc, unsigned& nx) {
;     const unsigned G = gridDim.x * gridDim.y * gridDim.z;
;     unsigned sum, cnt, mine, sp = 0u;
;     for (;;) {
;         sum = 0u; cnt = 0u; mine = 0u;
; #pragma unroll
;         for (unsigned j = 0; j < 16; ++j) { const unsigned c = xb_ld(&bar[XB_XCNT(j)]); sum += c; cnt += (c > 0u) ? 1u : 0u; mine = (j == x) ? c : mine; }
;         if (sum == G) break;
;         __builtin_amdgcn_s_sleep(1);
;         if ((++sp & 255u) == 0u) { if (xb_ld(&bar[XB_TMO])) break; if (sp > XB_SPIN_CAP) { atomicAdd(&bar[XB_TMO], 1u); break; } }
;     }
;     nloc = mine > 0u ? mine : 1u; nx = cnt > 0u ? cnt : 1u;
; }
.LBB0_43:
	global_load_dword v16, v17, s[6:7] sc1
	global_load_dword v1, v17, s[8:9] sc1
	global_load_dword v2, v17, s[10:11] sc1
	global_load_dword v3, v17, s[22:23] sc1
	global_load_dword v4, v17, s[24:25] sc1
	global_load_dword v5, v17, s[26:27] sc1
	global_load_dword v6, v17, s[30:31] sc1
	global_load_dword v7, v17, s[34:35] sc1
	global_load_dword v8, v17, s[36:37] sc1
	global_load_dword v9, v17, s[38:39] sc1
	global_load_dword v10, v17, s[40:41] sc1
	global_load_dword v11, v17, s[64:65] sc1
	global_load_dword v12, v17, s[66:67] sc1
	global_load_dword v13, v17, s[68:69] sc1
	global_load_dword v14, v17, s[70:71] sc1
	global_load_dword v15, v17, s[72:73] sc1
	s_mov_b64 s[74:75], -1
	s_mov_b64 s[76:77], -1
	s_waitcnt vmcnt(14)
	v_add_u32_e32 v18, v1, v16
	s_waitcnt vmcnt(13)
	v_add_u32_e32 v18, v18, v2
	s_waitcnt vmcnt(12)
	v_add_u32_e32 v18, v18, v3
	s_waitcnt vmcnt(11)
	v_add_u32_e32 v18, v18, v4
	s_waitcnt vmcnt(10)
	v_add_u32_e32 v18, v18, v5
	s_waitcnt vmcnt(9)
	v_add_u32_e32 v18, v18, v6
	s_waitcnt vmcnt(8)
	v_add_u32_e32 v18, v18, v7
	s_waitcnt vmcnt(7)
	v_add_u32_e32 v18, v18, v8
	s_waitcnt vmcnt(6)
	v_add_u32_e32 v18, v18, v9
	s_waitcnt vmcnt(5)
	v_add_u32_e32 v18, v18, v10
	s_waitcnt vmcnt(4)
	v_add_u32_e32 v18, v18, v11
	s_waitcnt vmcnt(3)
	v_add_u32_e32 v18, v18, v12
	s_waitcnt vmcnt(2)
	v_add_u32_e32 v18, v18, v13
	s_waitcnt vmcnt(1)
	v_add_u32_e32 v18, v18, v14
	s_waitcnt vmcnt(0)
	v_add_u32_e32 v18, v18, v15
	v_cmp_eq_u32_e32 vcc, s33, v18
	s_cbranch_vccnz .LBB0_42
	s_and_b32 s61, s60, 0xff
	s_cmp_eq_u32 s61, 0
	s_mov_b64 s[78:79], -1
	s_cbranch_scc0 .LBB0_47
	global_load_dword v18, v17, s[4:5] sc1
	s_waitcnt vmcnt(0)
	v_cmp_eq_u32_e32 vcc, 0, v18
	s_cbranch_vccnz .LBB0_49
	s_mov_b64 s[78:79], 0

; __device__ __forceinline__ unsigned xb_ld(unsigned* p)              { return __hip_atomic_load(p, __ATOMIC_RELAXED, __HIP_MEMORY_SCOPE_AGENT); }
; #define XB_SPIN(cond, bar) do { unsigned _sp = 0; while (cond) { __builtin_amdgcn_s_sleep(1); \
;     if ((++_sp & 255u) == 0u) { if (xb_ld(&(bar)[XB_TMO])) break; if (_sp > XB_SPIN_CAP) { atomicAdd(&(bar)[XB_TMO], 1u); break; } } } } while (0)
; __device__ __forceinline__ void xcd_barrier(const XcdBarrier& b) {
;     ...
;             else XB_SPIN(xb_ld(&bar[XB_TOPGEN]) == tg, bar);
.LBB0_61:
	s_and_b32 s34, s33, 0xff
	s_mov_b64 s[30:31], -1
	s_cmp_lg_u32 s34, 0
	s_mov_b64 s[36:37], -1
	s_cbranch_scc1 .LBB0_64
	global_load_dword v3, v1, s[10:11] sc1
	s_waitcnt vmcnt(0)
	v_cmp_eq_u32_e32 vcc, 0, v3
	s_cbranch_vccnz .LBB0_66
	s_mov_b64 s[36:37], 0
	s_mov_b64 s[34:35], -1

; __device__ __forceinline__ unsigned xb_ld(unsigned* p)              { return __hip_atomic_load(p, __ATOMIC_RELAXED, __HIP_MEMORY_SCOPE_AGENT); }
; #define XB_SPIN(cond, bar) do { unsigned _sp = 0; while (cond) { __builtin_amdgcn_s_sleep(1); \
;     if ((++_sp & 255u) == 0u) { if (xb_ld(&(bar)[XB_TMO])) break; if (_sp > XB_SPIN_CAP) { atomicAdd(&(bar)[XB_TMO], 1u); break; } } } } while (0)
; __device__ __forceinline__ void xcd_barrier(const XcdBarrier& b) {
;     ...
;             XB_SPIN(xb_ld(&bar[XB_XGEN(b.x)]) == gen, bar);
.LBB0_78:
	s_and_b32 s30, s33, 0xff
	s_cmp_lg_u32 s30, 0
	s_mov_b64 s[34:35], -1
	s_cbranch_scc1 .LBB0_81
	global_load_dword v2, v1, s[10:11] sc1
	s_waitcnt vmcnt(0)
	v_cmp_eq_u32_e32 vcc, 0, v2
	s_cbranch_vccnz .LBB0_83
	s_mov_b64 s[34:35], 0
	s_mov_b64 s[30:31], -1

; __device__ __forceinline__ unsigned xb_ld(unsigned* p)              { return __hip_atomic_load(p, __ATOMIC_RELAXED, __HIP_MEMORY_SCOPE_AGENT); }
; __device__ __forceinline__ void xcd_barrier_complete(unsigned* bar, unsigned x, unsigned& nloc, unsigned& nx) {
;     const unsigned G = gridDim.x * gridDim.y * gridDim.z;
;     unsigned sum, cnt, mine, sp = 0u;
;     for (;;) {
;         sum = 0u; cnt = 0u; mine = 0u;
; #pragma unroll
;         for (unsigned j = 0; j < 16; ++j) { const unsigned c = xb_ld(&bar[XB_XCNT(j)]); sum += c; cnt += (c > 0u) ? 1u : 0u; mine = (j == x) ? c : mine; }
;         if (sum == G) break;
;         __builtin_amdgcn_s_sleep(1);
;         if ((++sp & 255u) == 0u) { if (xb_ld(&bar[XB_TMO])) break; if (sp > XB_SPIN_CAP) { atomicAdd(&bar[XB_TMO], 1u); break; } }
;     }
;     nloc = mine > 0u ? mine : 1u; nx = cnt > 0u ? cnt : 1u;
; }
.LBB0_400:
	global_load_dword v16, v17, s[6:7] sc1
	global_load_dword v1, v17, s[8:9] sc1
	global_load_dword v2, v17, s[12:13] sc1
	global_load_dword v3, v17, s[14:15] sc1
	global_load_dword v4, v17, s[16:17] sc1
	global_load_dword v5, v17, s[18:19] sc1
	global_load_dword v6, v17, s[20:21] sc1
	global_load_dword v7, v17, s[22:23] sc1
	global_load_dword v8, v17, s[24:25] sc1
	global_load_dword v9, v17, s[26:27] sc1
	global_load_dword v10, v17, s[42:43] sc1
	global_load_dword v11, v17, s[68:69] sc1
	global_load_dword v12, v17, s[70:71] sc1
	global_load_dword v13, v17, s[72:73] sc1
	global_load_dword v14, v17, s[74:75] sc1
	global_load_dword v15, v17, s[76:77] sc1
	s_mov_b64 s[78:79], -1
	s_mov_b64 s[80:81], -1
	s_waitcnt vmcnt(14)
	v_add_u32_e32 v18, v1, v16
	s_waitcnt vmcnt(13)
	v_add_u32_e32 v18, v18, v2
	s_waitcnt vmcnt(12)
	v_add_u32_e32 v18, v18, v3
	s_waitcnt vmcnt(11)
	v_add_u32_e32 v18, v18, v4
	s_waitcnt vmcnt(10)
	v_add_u32_e32 v18, v18, v5
	s_waitcnt vmcnt(9)
	v_add_u32_e32 v18, v18, v6
	s_waitcnt vmcnt(8)
	v_add_u32_e32 v18, v18, v7
	s_waitcnt vmcnt(7)
	v_add_u32_e32 v18, v18, v8
	s_waitcnt vmcnt(6)
	v_add_u32_e32 v18, v18, v9
	s_waitcnt vmcnt(5)
	v_add_u32_e32 v18, v18, v10
	s_waitcnt vmcnt(4)
	v_add_u32_e32 v18, v18, v11
	s_waitcnt vmcnt(3)
	v_add_u32_e32 v18, v18, v12
	s_waitcnt vmcnt(2)
	v_add_u32_e32 v18, v18, v13
	s_waitcnt vmcnt(1)
	v_add_u32_e32 v18, v18, v14
	s_waitcnt vmcnt(0)
	v_add_u32_e32 v18, v18, v15
	v_cmp_eq_u32_e32 vcc, s30, v18
	s_cbranch_vccnz .LBB0_399
	s_and_b32 s33, s31, 0xff
	s_cmp_eq_u32 s33, 0
	s_mov_b64 s[82:83], -1
	s_cbranch_scc0 .LBB0_404
	global_load_dword v18, v17, s[4:5] sc1
	s_waitcnt vmcnt(0)
	v_cmp_eq_u32_e32 vcc, 0, v18
	s_cbranch_vccnz .LBB0_406
	s_mov_b64 s[82:83], 0

; __device__ __forceinline__ unsigned xb_ld(unsigned* p)              { return __hip_atomic_load(p, __ATOMIC_RELAXED, __HIP_MEMORY_SCOPE_AGENT); }
; #define XB_SPIN(cond, bar) do { unsigned _sp = 0; while (cond) { __builtin_amdgcn_s_sleep(1); \
;     if ((++_sp & 255u) == 0u) { if (xb_ld(&(bar)[XB_TMO])) break; if (_sp > XB_SPIN_CAP) { atomicAdd(&(bar)[XB_TMO], 1u); break; } } } } while (0)
; __device__ __forceinline__ void xcd_barrier(const XcdBarrier& b) {
;     ...
;             else XB_SPIN(xb_ld(&bar[XB_TOPGEN]) == tg, bar);
.LBB0_418:
	s_and_b32 s22, s26, 0xff
	s_mov_b64 s[20:21], -1
	s_cmp_lg_u32 s22, 0
	s_mov_b64 s[24:25], -1
	s_cbranch_scc1 .LBB0_421
	global_load_dword v3, v1, s[12:13] sc1
	s_waitcnt vmcnt(0)
	v_cmp_eq_u32_e32 vcc, 0, v3
	s_cbranch_vccnz .LBB0_423
	s_mov_b64 s[24:25], 0
	s_mov_b64 s[22:23], -1

; __device__ __forceinline__ unsigned xb_ld(unsigned* p)              { return __hip_atomic_load(p, __ATOMIC_RELAXED, __HIP_MEMORY_SCOPE_AGENT); }
; #define XB_SPIN(cond, bar) do { unsigned _sp = 0; while (cond) { __builtin_amdgcn_s_sleep(1); \
;     if ((++_sp & 255u) == 0u) { if (xb_ld(&(bar)[XB_TMO])) break; if (_sp > XB_SPIN_CAP) { atomicAdd(&(bar)[XB_TMO], 1u); break; } } } } while (0)
; __device__ __forceinline__ void xcd_barrier(const XcdBarrier& b) {
;     ...
;             XB_SPIN(xb_ld(&bar[XB_XGEN(b.x)]) == gen, bar);
.LBB0_435:
	s_and_b32 s20, s26, 0xff
	s_cmp_lg_u32 s20, 0
	s_mov_b64 s[22:23], -1
	s_cbranch_scc1 .LBB0_438
	global_load_dword v2, v1, s[12:13] sc1
	s_waitcnt vmcnt(0)
	v_cmp_eq_u32_e32 vcc, 0, v2
	s_cbranch_vccnz .LBB0_440
	s_mov_b64 s[22:23], 0
	s_mov_b64 s[20:21], -1

; __device__ __forceinline__ unsigned xb_ld(unsigned* p)              { return __hip_atomic_load(p, __ATOMIC_RELAXED, __HIP_MEMORY_SCOPE_AGENT); }
; __device__ __forceinline__ void xcd_barrier_complete(unsigned* bar, unsigned x, unsigned& nloc, unsigned& nx) {
;     const unsigned G = gridDim.x * gridDim.y * gridDim.z;
;     unsigned sum, cnt, mine, sp = 0u;
;     for (;;) {
;         sum = 0u; cnt = 0u; mine = 0u;
; #pragma unroll
;         for (unsigned j = 0; j < 16; ++j) { const unsigned c = xb_ld(&bar[XB_XCNT(j)]); sum += c; cnt += (c > 0u) ? 1u : 0u; mine = (j == x) ? c : mine; }
;         if (sum == G) break;
;         __builtin_amdgcn_s_sleep(1);
;         if ((++sp & 255u) == 0u) { if (xb_ld(&bar[XB_TMO])) break; if (sp > XB_SPIN_CAP) { atomicAdd(&bar[XB_TMO], 1u); break; } }
;     }
;     nloc = mine > 0u ? mine : 1u; nx = cnt > 0u ? cnt : 1u;
; }
.LBB0_497:
	global_load_dword v16, v17, s[6:7] sc1
	global_load_dword v1, v17, s[8:9] sc1
	global_load_dword v2, v17, s[10:11] sc1
	global_load_dword v3, v17, s[12:13] sc1
	global_load_dword v4, v17, s[14:15] sc1
	global_load_dword v5, v17, s[16:17] sc1
	global_load_dword v6, v17, s[18:19] sc1
	global_load_dword v7, v17, s[20:21] sc1
	global_load_dword v8, v17, s[22:23] sc1
	global_load_dword v9, v17, s[24:25] sc1
	global_load_dword v10, v17, s[26:27] sc1
	global_load_dword v11, v17, s[46:47] sc1
	global_load_dword v12, v17, s[48:49] sc1
	global_load_dword v13, v17, s[50:51] sc1
	global_load_dword v14, v17, s[78:79] sc1
	global_load_dword v15, v17, s[80:81] sc1
	s_mov_b64 s[82:83], -1
	s_mov_b64 s[84:85], -1
	s_waitcnt vmcnt(14)
	v_add_u32_e32 v18, v1, v16
	s_waitcnt vmcnt(13)
	v_add_u32_e32 v18, v18, v2
	s_waitcnt vmcnt(12)
	v_add_u32_e32 v18, v18, v3
	s_waitcnt vmcnt(11)
	v_add_u32_e32 v18, v18, v4
	s_waitcnt vmcnt(10)
	v_add_u32_e32 v18, v18, v5
	s_waitcnt vmcnt(9)
	v_add_u32_e32 v18, v18, v6
	s_waitcnt vmcnt(8)
	v_add_u32_e32 v18, v18, v7
	s_waitcnt vmcnt(7)
	v_add_u32_e32 v18, v18, v8
	s_waitcnt vmcnt(6)
	v_add_u32_e32 v18, v18, v9
	s_waitcnt vmcnt(5)
	v_add_u32_e32 v18, v18, v10
	s_waitcnt vmcnt(4)
	v_add_u32_e32 v18, v18, v11
	s_waitcnt vmcnt(3)
	v_add_u32_e32 v18, v18, v12
	s_waitcnt vmcnt(2)
	v_add_u32_e32 v18, v18, v13
	s_waitcnt vmcnt(1)
	v_add_u32_e32 v18, v18, v14
	s_waitcnt vmcnt(0)
	v_add_u32_e32 v18, v18, v15
	v_cmp_eq_u32_e32 vcc, s33, v18
	s_cbranch_vccnz .LBB0_496
	s_and_b32 s61, s60, 0xff
	s_cmp_eq_u32 s61, 0
	s_mov_b64 s[86:87], -1
	s_cbranch_scc0 .LBB0_501
	global_load_dword v18, v17, s[4:5] sc1
	s_waitcnt vmcnt(0)
	v_cmp_eq_u32_e32 vcc, 0, v18
	s_cbranch_vccnz .LBB0_503
	s_mov_b64 s[86:87], 0

; __device__ __forceinline__ unsigned xb_ld(unsigned* p)              { return __hip_atomic_load(p, __ATOMIC_RELAXED, __HIP_MEMORY_SCOPE_AGENT); }
; #define XB_SPIN(cond, bar) do { unsigned _sp = 0; while (cond) { __builtin_amdgcn_s_sleep(1); \
;     if ((++_sp & 255u) == 0u) { if (xb_ld(&(bar)[XB_TMO])) break; if (_sp > XB_SPIN_CAP) { atomicAdd(&(bar)[XB_TMO], 1u); break; } } } } while (0)
; __device__ __forceinline__ void xcd_barrier(const XcdBarrier& b) {
;     ...
;             else XB_SPIN(xb_ld(&bar[XB_TOPGEN]) == tg, bar);
.LBB0_515:
	s_and_b32 s20, s24, 0xff
	s_mov_b64 s[18:19], -1
	s_cmp_lg_u32 s20, 0
	s_mov_b64 s[22:23], -1
	s_cbranch_scc1 .LBB0_518
	global_load_dword v3, v1, s[10:11] sc1
	s_waitcnt vmcnt(0)
	v_cmp_eq_u32_e32 vcc, 0, v3
	s_cbranch_vccnz .LBB0_520
	s_mov_b64 s[22:23], 0
	s_mov_b64 s[20:21], -1

; __device__ __forceinline__ unsigned xb_ld(unsigned* p)              { return __hip_atomic_load(p, __ATOMIC_RELAXED, __HIP_MEMORY_SCOPE_AGENT); }
; #define XB_SPIN(cond, bar) do { unsigned _sp = 0; while (cond) { __builtin_amdgcn_s_sleep(1); \
;     if ((++_sp & 255u) == 0u) { if (xb_ld(&(bar)[XB_TMO])) break; if (_sp > XB_SPIN_CAP) { atomicAdd(&(bar)[XB_TMO], 1u); break; } } } } while (0)
; __device__ __forceinline__ void xcd_barrier(const XcdBarrier& b) {
;     ...
;             XB_SPIN(xb_ld(&bar[XB_XGEN(b.x)]) == gen, bar);
.LBB0_532:
	s_and_b32 s18, s24, 0xff
	s_cmp_lg_u32 s18, 0
	s_mov_b64 s[20:21], -1
	s_cbranch_scc1 .LBB0_535
	global_load_dword v2, v1, s[10:11] sc1
	s_waitcnt vmcnt(0)
	v_cmp_eq_u32_e32 vcc, 0, v2
	s_cbranch_vccnz .LBB0_537
	s_mov_b64 s[20:21], 0
	s_mov_b64 s[18:19], -1

; __device__ __forceinline__ void hgrn_wait(Frame& F, unsigned* cnt, int item) {
;     if (F.tid == 0) {
;         unsigned sp = 0;
;         while (__hip_atomic_load(cnt + 64 * (item >> 3), __ATOMIC_RELAXED, __HIP_MEMORY_SCOPE_AGENT) < 8u) { __builtin_amdgcn_s_sleep(2); if (++sp > (1u << 22)) break; }
;         __builtin_amdgcn_fence(__ATOMIC_ACQUIRE, "agent");
;         asm volatile("s_waitcnt vmcnt(0)" ::: "memory");
;     }
;     __syncthreads();
; }
.LBB0_556:
	global_load_dword v2, v155, s[12:13] sc1
	s_mov_b64 s[14:15], -1
	s_waitcnt vmcnt(0)
	v_cmp_lt_u32_e32 vcc, 7, v2
	s_cbranch_vccnz .LBB0_555
	global_load_dword v2, v155, s[12:13] sc1
	s_waitcnt vmcnt(0)
	v_cmp_gt_u32_e32 vcc, 8, v2
	s_cbranch_vccz .LBB0_555
	global_load_dword v2, v155, s[12:13] sc1
	s_waitcnt vmcnt(0)
	v_cmp_gt_u32_e32 vcc, 8, v2
	s_cbranch_vccz .LBB0_555
	global_load_dword v2, v155, s[12:13] sc1
	s_waitcnt vmcnt(0)
	v_cmp_gt_u32_e32 vcc, 8, v2
	s_cbranch_vccz .LBB0_555
	global_load_dword v2, v155, s[12:13] sc1
	s_waitcnt vmcnt(0)
	v_cmp_gt_u32_e32 vcc, 8, v2
	s_cbranch_vccz .LBB0_555
	s_add_i32 s8, s8, -5
	s_cmp_eq_u32 s8, 0
	s_cselect_b64 s[14:15], -1, 0
	s_branch .LBB0_555

; __device__ __forceinline__ unsigned xb_ld(unsigned* p)              { return __hip_atomic_load(p, __ATOMIC_RELAXED, __HIP_MEMORY_SCOPE_AGENT); }
; __device__ __forceinline__ void xcd_barrier_complete(unsigned* bar, unsigned x, unsigned& nloc, unsigned& nx) {
;     const unsigned G = gridDim.x * gridDim.y * gridDim.z;
;     unsigned sum, cnt, mine, sp = 0u;
;     for (;;) {
;         sum = 0u; cnt = 0u; mine = 0u;
; #pragma unroll
;         for (unsigned j = 0; j < 16; ++j) { const unsigned c = xb_ld(&bar[XB_XCNT(j)]); sum += c; cnt += (c > 0u) ? 1u : 0u; mine = (j == x) ? c : mine; }
;         if (sum == G) break;
;         __builtin_amdgcn_s_sleep(1);
;         if ((++sp & 255u) == 0u) { if (xb_ld(&bar[XB_TMO])) break; if (sp > XB_SPIN_CAP) { atomicAdd(&bar[XB_TMO], 1u); break; } }
;     }
;     nloc = mine > 0u ? mine : 1u; nx = cnt > 0u ? cnt : 1u;
; }
.LBB0_576:
	global_load_dword v16, v17, s[8:9] sc1
	global_load_dword v1, v17, s[10:11] sc1
	global_load_dword v2, v17, s[12:13] sc1
	global_load_dword v3, v17, s[14:15] sc1
	global_load_dword v4, v17, s[16:17] sc1
	global_load_dword v5, v17, s[18:19] sc1
	global_load_dword v6, v17, s[20:21] sc1
	global_load_dword v7, v17, s[22:23] sc1
	global_load_dword v8, v17, s[24:25] sc1
	global_load_dword v9, v17, s[26:27] sc1
	global_load_dword v10, v17, s[44:45] sc1
	global_load_dword v11, v17, s[46:47] sc1
	global_load_dword v12, v17, s[48:49] sc1
	global_load_dword v13, v17, s[50:51] sc1
	global_load_dword v14, v17, s[66:67] sc1
	global_load_dword v15, v17, s[68:69] sc1
	s_mov_b64 s[70:71], -1
	s_mov_b64 s[72:73], -1
	s_waitcnt vmcnt(14)
	v_add_u32_e32 v18, v1, v16
	s_waitcnt vmcnt(13)
	v_add_u32_e32 v18, v18, v2
	s_waitcnt vmcnt(12)
	v_add_u32_e32 v18, v18, v3
	s_waitcnt vmcnt(11)
	v_add_u32_e32 v18, v18, v4
	s_waitcnt vmcnt(10)
	v_add_u32_e32 v18, v18, v5
	s_waitcnt vmcnt(9)
	v_add_u32_e32 v18, v18, v6
	s_waitcnt vmcnt(8)
	v_add_u32_e32 v18, v18, v7
	s_waitcnt vmcnt(7)
	v_add_u32_e32 v18, v18, v8
	s_waitcnt vmcnt(6)
	v_add_u32_e32 v18, v18, v9
	s_waitcnt vmcnt(5)
	v_add_u32_e32 v18, v18, v10
	s_waitcnt vmcnt(4)
	v_add_u32_e32 v18, v18, v11
	s_waitcnt vmcnt(3)
	v_add_u32_e32 v18, v18, v12
	s_waitcnt vmcnt(2)
	v_add_u32_e32 v18, v18, v13
	s_waitcnt vmcnt(1)
	v_add_u32_e32 v18, v18, v14
	s_waitcnt vmcnt(0)
	v_add_u32_e32 v18, v18, v15
	v_cmp_eq_u32_e32 vcc, s30, v18
	s_cbranch_vccnz .LBB0_575
	s_and_b32 s33, s31, 0xff
	s_cmp_eq_u32 s33, 0
	s_mov_b64 s[74:75], -1
	s_cbranch_scc0 .LBB0_580
	global_load_dword v18, v17, s[6:7] sc1
	s_waitcnt vmcnt(0)
	v_cmp_eq_u32_e32 vcc, 0, v18
	s_cbranch_vccnz .LBB0_582
	s_mov_b64 s[74:75], 0

; __device__ __forceinline__ unsigned xb_ld(unsigned* p)              { return __hip_atomic_load(p, __ATOMIC_RELAXED, __HIP_MEMORY_SCOPE_AGENT); }
; __device__ __forceinline__ void xcd_barrier_complete(unsigned* bar, unsigned x, unsigned& nloc, unsigned& nx) {
;     const unsigned G = gridDim.x * gridDim.y * gridDim.z;
;     unsigned sum, cnt, mine, sp = 0u;
;     for (;;) {
;         sum = 0u; cnt = 0u; mine = 0u;
; #pragma unroll
;         for (unsigned j = 0; j < 16; ++j) { const unsigned c = xb_ld(&bar[XB_XCNT(j)]); sum += c; cnt += (c > 0u) ? 1u : 0u; mine = (j == x) ? c : mine; }
;         if (sum == G) break;
;         __builtin_amdgcn_s_sleep(1);
;         if ((++sp & 255u) == 0u) { if (xb_ld(&bar[XB_TMO])) break; if (sp > XB_SPIN_CAP) { atomicAdd(&bar[XB_TMO], 1u); break; } }
;     }
;     nloc = mine > 0u ? mine : 1u; nx = cnt > 0u ? cnt : 1u;
; }
.LBB0_673:
	global_load_dword v16, v17, s[6:7] sc1
	global_load_dword v1, v17, s[10:11] sc1
	global_load_dword v2, v17, s[12:13] sc1
	global_load_dword v3, v17, s[14:15] sc1
	global_load_dword v4, v17, s[16:17] sc1
	global_load_dword v5, v17, s[18:19] sc1
	global_load_dword v6, v17, s[20:21] sc1
	global_load_dword v7, v17, s[22:23] sc1
	global_load_dword v8, v17, s[24:25] sc1
	global_load_dword v9, v17, s[26:27] sc1
	global_load_dword v10, v17, s[40:41] sc1
	global_load_dword v11, v17, s[44:45] sc1
	global_load_dword v12, v17, s[46:47] sc1
	global_load_dword v13, v17, s[48:49] sc1
	global_load_dword v14, v17, s[50:51] sc1
	global_load_dword v15, v17, s[64:65] sc1
	s_mov_b64 s[66:67], -1
	s_mov_b64 s[68:69], -1
	s_waitcnt vmcnt(14)
	v_add_u32_e32 v18, v1, v16
	s_waitcnt vmcnt(13)
	v_add_u32_e32 v18, v18, v2
	s_waitcnt vmcnt(12)
	v_add_u32_e32 v18, v18, v3
	s_waitcnt vmcnt(11)
	v_add_u32_e32 v18, v18, v4
	s_waitcnt vmcnt(10)
	v_add_u32_e32 v18, v18, v5
	s_waitcnt vmcnt(9)
	v_add_u32_e32 v18, v18, v6
	s_waitcnt vmcnt(8)
	v_add_u32_e32 v18, v18, v7
	s_waitcnt vmcnt(7)
	v_add_u32_e32 v18, v18, v8
	s_waitcnt vmcnt(6)
	v_add_u32_e32 v18, v18, v9
	s_waitcnt vmcnt(5)
	v_add_u32_e32 v18, v18, v10
	s_waitcnt vmcnt(4)
	v_add_u32_e32 v18, v18, v11
	s_waitcnt vmcnt(3)
	v_add_u32_e32 v18, v18, v12
	s_waitcnt vmcnt(2)
	v_add_u32_e32 v18, v18, v13
	s_waitcnt vmcnt(1)
	v_add_u32_e32 v18, v18, v14
	s_waitcnt vmcnt(0)
	v_add_u32_e32 v18, v18, v15
	v_cmp_eq_u32_e32 vcc, s30, v18
	s_cbranch_vccnz .LBB0_672
	s_and_b32 s33, s31, 0xff
	s_cmp_eq_u32 s33, 0
	s_mov_b64 s[70:71], -1
	s_cbranch_scc0 .LBB0_677
	global_load_dword v18, v17, s[4:5] sc1
	s_waitcnt vmcnt(0)
	v_cmp_eq_u32_e32 vcc, 0, v18
	s_cbranch_vccnz .LBB0_679
	s_mov_b64 s[70:71], 0

; __device__ __forceinline__ unsigned xb_ld(unsigned* p)              { return __hip_atomic_load(p, __ATOMIC_RELAXED, __HIP_MEMORY_SCOPE_AGENT); }
; __device__ __forceinline__ void xcd_barrier_complete(unsigned* bar, unsigned x, unsigned& nloc, unsigned& nx) {
;     const unsigned G = gridDim.x * gridDim.y * gridDim.z;
;     unsigned sum, cnt, mine, sp = 0u;
;     for (;;) {
;         sum = 0u; cnt = 0u; mine = 0u;
; #pragma unroll
;         for (unsigned j = 0; j < 16; ++j) { const unsigned c = xb_ld(&bar[XB_XCNT(j)]); sum += c; cnt += (c > 0u) ? 1u : 0u; mine = (j == x) ? c : mine; }
;         if (sum == G) break;
;         __builtin_amdgcn_s_sleep(1);
;         if ((++sp & 255u) == 0u) { if (xb_ld(&bar[XB_TMO])) break; if (sp > XB_SPIN_CAP) { atomicAdd(&bar[XB_TMO], 1u); break; } }
;     }
;     nloc = mine > 0u ? mine : 1u; nx = cnt > 0u ? cnt : 1u;
; }
.LBB0_790:
	global_load_dword v16, v17, s[8:9] sc1
	global_load_dword v1, v17, s[10:11] sc1
	global_load_dword v2, v17, s[12:13] sc1
	global_load_dword v3, v17, s[14:15] sc1
	global_load_dword v4, v17, s[16:17] sc1
	global_load_dword v5, v17, s[18:19] sc1
	global_load_dword v6, v17, s[20:21] sc1
	global_load_dword v7, v17, s[22:23] sc1
	global_load_dword v8, v17, s[24:25] sc1
	global_load_dword v9, v17, s[26:27] sc1
	global_load_dword v10, v17, s[28:29] sc1
	global_load_dword v11, v17, s[30:31] sc1
	global_load_dword v12, v17, s[36:37] sc1
	global_load_dword v13, v17, s[38:39] sc1
	global_load_dword v14, v17, s[40:41] sc1
	global_load_dword v15, v17, s[44:45] sc1
	s_mov_b64 s[46:47], -1
	s_mov_b64 s[48:49], -1
	s_waitcnt vmcnt(14)
	v_add_u32_e32 v18, v1, v16
	s_waitcnt vmcnt(13)
	v_add_u32_e32 v18, v18, v2
	s_waitcnt vmcnt(12)
	v_add_u32_e32 v18, v18, v3
	s_waitcnt vmcnt(11)
	v_add_u32_e32 v18, v18, v4
	s_waitcnt vmcnt(10)
	v_add_u32_e32 v18, v18, v5
	s_waitcnt vmcnt(9)
	v_add_u32_e32 v18, v18, v6
	s_waitcnt vmcnt(8)
	v_add_u32_e32 v18, v18, v7
	s_waitcnt vmcnt(7)
	v_add_u32_e32 v18, v18, v8
	s_waitcnt vmcnt(6)
	v_add_u32_e32 v18, v18, v9
	s_waitcnt vmcnt(5)
	v_add_u32_e32 v18, v18, v10
	s_waitcnt vmcnt(4)
	v_add_u32_e32 v18, v18, v11
	s_waitcnt vmcnt(3)
	v_add_u32_e32 v18, v18, v12
	s_waitcnt vmcnt(2)
	v_add_u32_e32 v18, v18, v13
	s_waitcnt vmcnt(1)
	v_add_u32_e32 v18, v18, v14
	s_waitcnt vmcnt(0)
	v_add_u32_e32 v18, v18, v15
	v_cmp_eq_u32_e32 vcc, s33, v18
	s_cbranch_vccnz .LBB0_789
	s_and_b32 s46, s52, 0xff
	s_cmp_eq_u32 s46, 0
	s_mov_b64 s[46:47], -1
	s_mov_b64 s[50:51], -1
	s_cbranch_scc0 .LBB0_794
	global_load_dword v18, v17, s[4:5] sc1
	s_waitcnt vmcnt(0)
	v_cmp_eq_u32_e32 vcc, 0, v18
	s_cbranch_vccnz .LBB0_796
	s_mov_b64 s[50:51], 0
